# attention item prologue: abs-max of the QK-norm gain tables via one lane-distributed load per table plus DPP/readlane wave max instead of 8 serialized uniform-load round trips (MLA and MIXA items)
# speedup vs baseline: 1.0054x; 1.0003x over previous
; template <int DQK, bool MIXA, bool PIPE>
; DI void attn_item(const Params& P, int layer, char* smem, int b, int h, int qt) {
;     ...
;   {
;     const float* g1 = MIXA ? (P.a_q_norm + layer * 64) : (P.b_q_norm + layer * 96);
;     const float* g2 = MIXA ? (P.a_k_norm + layer * 64) : (P.b_k_norm + layer * 96);
;     float a1 = 0.f, a2 = 0.f;
;     for (int i = 0; i < DQK; ++i) { a1 = fmaxf(a1, fabsf(g1[i])); a2 = fmaxf(a2, fabsf(g2[i])); }
;     mfix = (float)DQK * 1.02f * a1 * a2 * sl2;
;     if (MIXA) {
;       const float b15 = P.rel_bias[15 * 8 + h];
;       float bm = 0.f;
;       for (int i = 0; i < 32; ++i) bm = fmaxf(bm, P.rel_bias[i * 8 + h] - b15);
;       mfix += bm * LOG2E;
;     }
;   }
;   if (MIXA) {
;     const int rel = tid - 192;
;     const float b15 = P.rel_bias[15 * 8 + h];
;     biasT[tid] = (P.rel_bias[t5_bucket(rel) * 8 + h] - b15) * LOG2E;
;   }
;   bf16x8 qf[NS];
; #pragma unroll
;   for (int s = 0; s < NS; ++s) qf[s] = *(const bf16x8*)(Qp + tokq * ldq + 16 * s + 8 * H);
;   const int nkt = 2 * qt + 2;
;   unsigned koff[NKI], voff[2];
; #pragma unroll
;   for (int i = 0; i < NKI; ++i) {
;     const int e = (w * NKI + i) * 64 + lane;
;     const int row = e / KCH, slot = e % KCH;
;     const int c = slot ^ (MIXA ? ((row >> 1) & 7) : ((row >> 2) & 3));
;     koff[i] = (unsigned)((row * ldk + c * 8) * 2);
;   }
; #pragma unroll
;   for (int i = 0; i < 2; ++i) {
;     const int e = (w * 2 + i) * 64 + lane;
;     const int row = e >> 3, slot = e & 7;
;     const int c = slot ^ ((row >> 1) & 7);
;     voff[i] = (unsigned)((row * S_ + c * 8) * 2);
;   }
;   unsigned mwn[2] = {0u, 0u};
;   auto issue_loads = [&](int kt) __attribute__((always_inline)) {
;     const char* kbp = (const char*)(Kp + (size_t)(kt * 64) * ldk);
;     const char* vbp = (const char*)(VT + kt * 64);
;     char* sk = smem + (kt & 1) * STG_B;
; #pragma unroll
;     for (int i = 0; i < NKI; ++i)
;       __builtin_amdgcn_global_load_lds((const unsigned*)(kbp + koff[i]), (unsigned*)(sk + (w * NKI + i) * 1024), 16, 0, 0);
; #pragma unroll
;     for (int i = 0; i < 2; ++i)
;       __builtin_amdgcn_global_load_lds((const unsigned*)(vbp + voff[i]), (unsigned*)(sk + KTILE_B + (w * 2 + i) * 1024), 16, 0, 0);
;     if (MIXA) {
;       if (kt <= cw) {
;         const unsigned* mp = mask + mask_base(b, cw) + (2 * kt) * 64 + (qpos & 63);
;         mwn[0] = mp[0]; mwn[1] = mp[64];
.LBB0_81:
	s_or_b64 exec, exec, s[18:19]
	s_mov_b64 s[18:19], src_shared_base
	v_mov_b32_e32 v139, s19
	s_waitcnt lgkmcnt(0)
	s_barrier
	flat_load_dword v0, v[138:139] sc0 sc1
	s_waitcnt vmcnt(0)
	s_mov_b64 s[18:19], -1
	s_waitcnt lgkmcnt(0)
	s_barrier
	v_cmp_gt_i32_e32 vcc, s24, v0
	s_and_saveexec_b64 s[52:53], vcc
	s_cbranch_execz .LBB0_76
	s_movk_i32 s18, 0x7f
	v_bitop3_b32 v34, v0, s18, v0 bitop3:0xc
	v_bfe_u32 v35, v0, 7, 1
	v_and_b32_e32 v0, 0x100, v0
	v_cmp_ne_u32_e32 vcc, 0, v0
	s_and_saveexec_b64 s[18:19], vcc
	s_xor_b64 s[42:43], exec, s[18:19]
	s_cbranch_execz .LBB0_92
	v_mov_b32_e32 v0, v161
	v_and_b32_e32 v4, 63, v161
	v_lshlrev_b32_e32 v4, 2, v4
	v_and_b32_e32 v5, 0x7c, v4
	s_mov_b32 s18, s65
	s_mov_b32 s19, s66
	s_mov_b32 s20, s67
	s_mov_b32 s21, s68
	global_load_dword v2, v4, s[18:19]
	global_load_dword v6, v5, s[18:19] offset:256
	global_load_dword v1, v4, s[20:21]
	global_load_dword v7, v5, s[20:21] offset:256
	s_waitcnt vmcnt(0)
	v_max_f32_e64 v2, |v2|, |v6|
	v_max_f32_e64 v1, |v1|, |v7|
	s_nop 1
	v_max_f32_dpp v2, v2, v2 quad_perm:[1,0,3,2] row_mask:0xf bank_mask:0xf
	v_max_f32_dpp v1, v1, v1 quad_perm:[1,0,3,2] row_mask:0xf bank_mask:0xf
	s_nop 1
	v_max_f32_dpp v2, v2, v2 quad_perm:[2,3,0,1] row_mask:0xf bank_mask:0xf
	v_max_f32_dpp v1, v1, v1 quad_perm:[2,3,0,1] row_mask:0xf bank_mask:0xf
	s_nop 1
	v_max_f32_dpp v2, v2, v2 row_half_mirror row_mask:0xf bank_mask:0xf
	v_max_f32_dpp v1, v1, v1 row_half_mirror row_mask:0xf bank_mask:0xf
	s_nop 1
	v_max_f32_dpp v2, v2, v2 row_mirror row_mask:0xf bank_mask:0xf
	v_max_f32_dpp v1, v1, v1 row_mirror row_mask:0xf bank_mask:0xf
	s_nop 1
	v_readlane_b32 s18, v2, 0
	v_readlane_b32 s19, v2, 16
	v_readlane_b32 s20, v2, 32
	v_readlane_b32 s21, v2, 48
	v_mov_b32_e32 v2, s18
	v_max_f32_e32 v2, s19, v2
	v_max_f32_e32 v2, s20, v2
	v_max_f32_e32 v2, s21, v2
	v_readlane_b32 s18, v1, 0
	v_readlane_b32 s19, v1, 16
	v_readlane_b32 s20, v1, 32
	v_readlane_b32 s21, v1, 48
	v_mov_b32_e32 v1, s18
	v_max_f32_e32 v1, s19, v1
	v_max_f32_e32 v1, s20, v1
	v_max_f32_e32 v1, s21, v1
	v_lshl_or_b32 v3, v35, 3, s87
	v_ashrrev_i32_e32 v18, 6, v0
	v_mul_u32_u24_e32 v136, 0x300000, v3
	v_lshlrev_b32_e32 v3, 7, v34
	v_lshl_add_u32 v12, v18, 5, v3
	v_and_b32_e32 v20, 31, v0
	v_readlane_b32 s0, v252, 57
	v_or_b32_e32 v10, v12, v20
	v_lshlrev_b32_e32 v6, 14, v35
	v_readlane_b32 s1, v252, 58
	v_ashrrev_i32_e32 v11, 31, v10
	v_mov_b32_e32 v7, v137
	v_mul_f32_e32 v2, 0x42c3d70a, v2
	v_lshl_add_u64 v[8:9], s[0:1], 0, v[136:137]
	v_lshl_add_u64 v[112:113], v[10:11], 0, v[6:7]
	v_mul_f32_e32 v1, v1, v2
	v_mov_b64_e32 v[2:3], s[62:63]
	s_movk_i32 s0, 0x600
	v_bfe_u32 v139, v0, 5, 1
	v_mad_u64_u32 v[2:3], s[18:19], v112, s0, v[2:3]
	v_mad_i32_i24 v3, v113, s0, v3
	v_lshlrev_b32_e32 v6, 4, v139
	v_lshl_add_u64 v[2:3], v[2:3], 0, v[6:7]
	v_and_b32_e32 v21, 63, v0
	global_load_dwordx4 v[84:87], v[2:3], off
	global_load_dwordx4 v[80:83], v[2:3], off offset:32
	global_load_dwordx4 v[76:79], v[2:3], off offset:64
	global_load_dwordx4 v[72:75], v[2:3], off offset:96
	global_load_dwordx4 v[68:71], v[2:3], off offset:128
	global_load_dwordx4 v[64:67], v[2:3], off offset:160
	v_mul_lo_u32 v2, v18, s72
	v_or_b32_e32 v3, v2, v21
	s_mov_b32 s0, 0x2aaaaaab
	v_mul_hi_i32 v2, v3, s0
	v_lshrrev_b32_e32 v6, 31, v2
	v_ashrrev_i32_e32 v2, 1, v2
	v_add_u32_e32 v2, v2, v6
	v_mul_lo_u32 v6, v2, 12
	v_sub_u32_e32 v6, v3, v6
	v_lshrrev_b32_e32 v7, 2, v2
	v_bitop3_b32 v6, v7, v6, 3 bitop3:0x6c
	v_mul_lo_u32 v2, v2, s72
	v_lshl_add_u32 v2, v6, 4, v2
	v_add_u32_e32 v6, 64, v3
	v_mul_hi_i32 v7, v6, s0
	v_lshrrev_b32_e32 v10, 31, v7
	v_ashrrev_i32_e32 v7, 1, v7
	v_add_u32_e32 v7, v7, v10
	v_mul_lo_u32 v10, v7, 12
	v_sub_u32_e32 v6, v6, v10
	v_lshrrev_b32_e32 v10, 2, v7
	v_bitop3_b32 v6, v10, v6, 3 bitop3:0x6c
	v_mul_lo_u32 v7, v7, s72
	v_add_u32_e32 v3, 0x80, v3
	v_lshl_add_u32 v6, v6, 4, v7
	v_mul_hi_i32 v7, v3, s0
	v_lshrrev_b32_e32 v10, 31, v7
	v_ashrrev_i32_e32 v7, 1, v7
	v_add_u32_e32 v7, v7, v10
	v_mul_lo_u32 v10, v7, 12
	v_sub_u32_e32 v3, v3, v10
	v_lshrrev_b32_e32 v10, 2, v7
	v_bitop3_b32 v3, v10, v3, 3 bitop3:0x6c
	v_mul_lo_u32 v7, v7, s72
	v_lshl_add_u32 v10, v3, 4, v7
	v_mul_f32_e32 v114, 0x3e16c740, v1
	v_lshl_or_b32 v1, v18, 7, v21
	v_lshlrev_b32_e32 v3, 4, v0
	v_lshlrev_b32_e32 v7, 12, v1
	v_bitop3_b32 v22, v21, s92, v3 bitop3:0x48
	v_or_b32_e32 v1, 64, v1
	v_ashrrev_i32_e32 v127, 6, v12
	v_and_or_b32 v12, v7, s25, v22
	v_lshlrev_b32_e32 v7, 12, v1
	v_bitop3_b32 v1, v1, s92, v3 bitop3:0x48
	s_movk_i32 s0, 0x8000
	v_lshlrev_b32_e32 v19, 24, v35
	v_and_or_b32 v14, v7, s0, v1
	v_readlane_b32 s0, v252, 59
	v_or_b32_e32 v4, s88, v19
	v_mov_b32_e32 v5, v137
	v_readlane_b32 s1, v252, 60
	v_mov_b32_e32 v3, v137
	v_lshl_add_u64 v[16:17], v[8:9], 0, v[2:3]
	v_lshl_add_u64 v[4:5], s[0:1], 0, v[4:5]
	s_movk_i32 s0, 0xc00
	v_mul_lo_u32 v132, v18, s0
	v_add_u32_e32 v1, 0x400, v132
	v_readfirstlane_b32 s18, v132
	s_mov_b32 m0, s18
	v_mov_b32_e32 v7, v137
	v_readfirstlane_b32 s18, v1
	v_add_u32_e32 v1, 0x800, v132
	v_lshlrev_b32_e32 v135, 11, v18
	global_load_lds_dwordx4 v[16:17], off
	v_lshl_add_u64 v[16:17], v[8:9], 0, v[6:7]
	s_mov_b32 m0, s18
	v_mov_b32_e32 v11, v137
	v_readfirstlane_b32 s18, v1
	v_add_u32_e32 v1, 0x3000, v135
	global_load_lds_dwordx4 v[16:17], off
	v_lshl_add_u64 v[8:9], v[8:9], 0, v[10:11]
	s_mov_b32 m0, s18
	v_mov_b32_e32 v13, v137
	v_readfirstlane_b32 s18, v1
	v_add_u32_e32 v1, 0x3400, v135
	global_load_lds_dwordx4 v[8:9], off
	v_lshl_add_u64 v[8:9], v[4:5], 0, v[12:13]
	s_mov_b32 m0, s18
	v_mov_b32_e32 v15, v137
	v_readfirstlane_b32 s18, v1
	global_load_lds_dwordx4 v[8:9], off
	v_lshl_add_u64 v[4:5], v[4:5], 0, v[14:15]
	s_mov_b32 m0, s18
	v_and_b32_e32 v1, 19, v0
	global_load_lds_dwordx4 v[4:5], off
	v_lshlrev_b32_e32 v4, 1, v0
	v_lshrrev_b32_e32 v5, 1, v0
	v_and_b32_e32 v4, 8, v4
	v_and_b32_e32 v8, 4, v5
	v_or3_b32 v1, v4, v1, v8
	v_lshrrev_b32_e32 v4, 2, v1
	v_mul_u32_u24_e32 v141, 0xc0, v1
	v_or_b32_e32 v1, 2, v139
	v_bitop3_b32 v1, v4, v1, 3 bitop3:0x6c
	v_lshlrev_b32_e32 v142, 4, v1
	v_or_b32_e32 v1, 4, v139
	v_bitop3_b32 v1, v4, v1, 3 bitop3:0x6c
	v_lshlrev_b32_e32 v143, 4, v1
	v_or_b32_e32 v1, 6, v139
	v_bitop3_b32 v1, v4, v1, 3 bitop3:0x6c
	v_lshlrev_b32_e32 v144, 4, v1
	v_or_b32_e32 v1, 8, v139
	v_bitop3_b32 v1, v4, v1, 3 bitop3:0x6c
	v_lshlrev_b32_e32 v145, 4, v1
	v_or_b32_e32 v1, 10, v139
	v_bfe_u32 v0, v0, 1, 3
	v_bitop3_b32 v1, v4, v1, 3 bitop3:0x6c
	v_lshlrev_b32_e32 v146, 4, v1
	v_bitop3_b32 v1, v139, v0, 4 bitop3:0x36
	v_lshlrev_b32_e32 v130, 4, v1
	v_bitop3_b32 v1, v139, v5, 7 bitop3:0x78
	v_bitop3_b32 v8, v4, v139, 3 bitop3:0x6c
	v_lshlrev_b32_e32 v134, 4, v1
	v_bitop3_b32 v1, v139, v0, 2 bitop3:0x36
	v_bitop3_b32 v0, v139, v0, 6 bitop3:0x36
	v_lshlrev_b32_e32 v4, 12, v21
	s_waitcnt vmcnt(0)
; template <int DQK, bool MIXA, bool PIPE>
; DI void attn_item(const Params& P, int layer, char* smem, int b, int h, int qt) {
;     ...
;   f32x16 o[2];
; #pragma unroll
;   for (int d = 0; d < 2; ++d)
; #pragma unroll
;     for (int i = 0; i < 16; ++i) o[d][i] = 0.f;
;   float l = 0.f;
;   const int pr = (l31 & ~12) | ((l31 & 4) << 1) | ((l31 & 8) >> 1);
;   const int swk = MIXA ? ((pr >> 1) & 7) : ((pr >> 2) & 3), swv = (l31 >> 1) & 7;
;   asm volatile("s_waitcnt vmcnt(0)" ::: "memory");
;   __syncthreads();
	v_lshlrev_b32_e32 v133, 4, v1
	v_lshlrev_b32_e32 v131, 4, v0
	v_or_b32_e32 v0, s86, v19
	v_mov_b32_e32 v1, v137
	s_mov_b64 s[18:19], 0x1d000080
	v_lshl_or_b32 v4, v18, 19, v4
	v_lshlrev_b32_e32 v128, 1, v34
	v_lshl_add_u64 v[0:1], v[0:1], 0, s[18:19]
	v_and_or_b32 v4, v4, s25, v22
	v_mov_b32_e32 v5, v137
	v_or_b32_e32 v136, 0x18003000, v136
	v_mov_b32_e32 v126, 0
	v_lshlrev_b32_e32 v129, 7, v20
	v_mov_b32_e32 v115, v114
	v_sub_f32_e32 v228, 0, v114
	v_sub_f32_e32 v229, 0, v114
	v_sub_f32_e32 v230, 0, v114
	v_sub_f32_e32 v231, 0, v114
	v_sub_f32_e32 v232, 0, v114
	v_sub_f32_e32 v233, 0, v114
	v_sub_f32_e32 v234, 0, v114
	v_sub_f32_e32 v235, 0, v114
	v_sub_f32_e32 v236, 0, v114
	v_sub_f32_e32 v237, 0, v114
	v_sub_f32_e32 v238, 0, v114
	v_sub_f32_e32 v239, 0, v114
	v_sub_f32_e32 v240, 0, v114
	v_sub_f32_e32 v241, 0, v114
	v_sub_f32_e32 v242, 0, v114
	v_sub_f32_e32 v243, 0, v114
	v_lshlrev_b32_e32 v140, 4, v8
	v_or_b32_e32 v147, 1, v128
	v_lshl_add_u64 v[116:117], v[0:1], 0, v[4:5]
	v_lshl_add_u64 v[118:119], v[0:1], 0, v[14:15]
	s_mov_b32 s22, 0
	v_lshl_add_u64 v[120:121], v[136:137], 0, v[2:3]
	v_lshl_add_u64 v[122:123], v[136:137], 0, v[6:7]
	v_lshl_add_u64 v[124:125], v[136:137], 0, v[10:11]
	s_mov_b64 s[44:45], 0
	v_mov_b32_e32 v0, 0
	v_mov_b32_e32 v1, v126
	v_mov_b32_e32 v2, v126
	v_mov_b32_e32 v3, v126
	v_mov_b32_e32 v4, v126
	v_mov_b32_e32 v5, v126
	v_mov_b32_e32 v6, v126
	v_mov_b32_e32 v7, v126
	v_mov_b32_e32 v8, v126
	v_mov_b32_e32 v9, v126
	v_mov_b32_e32 v10, v126
	v_mov_b32_e32 v11, v126
	v_mov_b32_e32 v12, v126
	v_mov_b32_e32 v13, v126
	v_mov_b32_e32 v14, v126
	v_mov_b32_e32 v15, v126
	v_mov_b32_e32 v16, v126
	v_mov_b32_e32 v17, v126
	v_mov_b32_e32 v18, v126
	v_mov_b32_e32 v19, v126
	v_mov_b32_e32 v20, v126
	v_mov_b32_e32 v21, v126
	v_mov_b32_e32 v22, v126
	v_mov_b32_e32 v23, v126
	v_mov_b32_e32 v24, v126
	v_mov_b32_e32 v25, v126
	v_mov_b32_e32 v26, v126
	v_mov_b32_e32 v27, v126
	v_mov_b32_e32 v28, v126
	v_mov_b32_e32 v29, v126
	v_mov_b32_e32 v30, v126
	v_mov_b32_e32 v31, v126
	s_waitcnt vmcnt(0) lgkmcnt(0)
	s_barrier
	v_readfirstlane_b32 s32, v132
	v_readfirstlane_b32 s73, v135
	s_mov_b64 s[36:37], s[74:75]
	s_mov_b64 s[38:39], s[74:75]
	v_add_u32_e32 v168, v141, v140
	v_add_u32_e32 v170, v141, v142
	v_add_u32_e32 v172, v141, v143
	v_add_u32_e32 v174, v141, v144
	v_add_u32_e32 v176, v141, v145
	v_add_u32_e32 v244, v141, v146
	v_add_u32_e32 v245, v129, v134
	v_add_u32_e32 v246, v129, v133
	v_add_u32_e32 v247, v129, v130
	v_add_u32_e32 v248, v129, v131
	v_readfirstlane_b32 s78, v127
	v_readfirstlane_b32 s79, v147
	s_branch .LBB0_87

; DI int t5_bucket(int rel) {
;   const int n = rel < 0 ? -rel : rel;
;   int bkt;
;   if (n < 8) bkt = n; else if (n < 12) bkt = 8; else if (n < 16) bkt = 9; else if (n < 23) bkt = 10; else if (n < 32) bkt = 11;
;   else if (n < 46) bkt = 12; else if (n < 64) bkt = 13; else if (n < 91) bkt = 14; else bkt = 15;
; template <int DQK, bool MIXA, bool PIPE>
; DI void attn_item(const Params& P, int layer, char* smem, int b, int h, int qt) {
;     ...
;   {
;     const float* g1 = MIXA ? (P.a_q_norm + layer * 64) : (P.b_q_norm + layer * 96);
;     const float* g2 = MIXA ? (P.a_k_norm + layer * 64) : (P.b_k_norm + layer * 96);
;     float a1 = 0.f, a2 = 0.f;
;     for (int i = 0; i < DQK; ++i) { a1 = fmaxf(a1, fabsf(g1[i])); a2 = fmaxf(a2, fabsf(g2[i])); }
;     mfix = (float)DQK * 1.02f * a1 * a2 * sl2;
;     if (MIXA) {
;       const float b15 = P.rel_bias[15 * 8 + h];
;       float bm = 0.f;
;       for (int i = 0; i < 32; ++i) bm = fmaxf(bm, P.rel_bias[i * 8 + h] - b15);
;       mfix += bm * LOG2E;
;     }
;   }
;   if (MIXA) {
;     const int rel = tid - 192;
;     const float b15 = P.rel_bias[15 * 8 + h];
;     biasT[tid] = (P.rel_bias[t5_bucket(rel) * 8 + h] - b15) * LOG2E;
.LBB0_92:
	s_andn2_saveexec_b64 s[54:55], s[42:43]
	s_cbranch_execz .LBB0_75
	v_mov_b32_e32 v10, v161
	v_and_b32_e32 v0, 63, v161
	v_lshlrev_b32_e32 v0, 2, v0
	s_mov_b32 s18, s69
	s_mov_b32 s19, s70
	s_mov_b32 s20, s71
	s_mov_b32 s21, s84
	global_load_dword v12, v0, s[18:19]
	global_load_dword v11, v0, s[20:21]
	global_load_dword v47, v137, s[16:17]
	global_load_dword v48, v137, s[16:17] offset:32
	global_load_dword v44, v137, s[16:17] offset:64
	global_load_dword v45, v137, s[16:17] offset:96
	global_load_dword v42, v137, s[16:17] offset:128
	global_load_dword v43, v137, s[16:17] offset:160
	global_load_dword v38, v137, s[16:17] offset:192
	global_load_dword v39, v137, s[16:17] offset:224
	global_load_dword v13, v137, s[16:17] offset:480
	global_load_dword v40, v137, s[16:17] offset:256
	global_load_dword v41, v137, s[16:17] offset:288
	global_load_dword v36, v137, s[16:17] offset:320
	global_load_dword v37, v137, s[16:17] offset:352
	global_load_dword v32, v137, s[16:17] offset:384
	global_load_dword v33, v137, s[16:17] offset:416
	global_load_dword v31, v137, s[16:17] offset:448
	global_load_dword v28, v137, s[16:17] offset:512
	global_load_dword v29, v137, s[16:17] offset:544
	global_load_dword v26, v137, s[16:17] offset:576
	global_load_dword v27, v137, s[16:17] offset:608
	global_load_dword v24, v137, s[16:17] offset:640
	global_load_dword v25, v137, s[16:17] offset:672
	global_load_dword v22, v137, s[16:17] offset:704
	global_load_dword v23, v137, s[16:17] offset:736
	global_load_dword v20, v137, s[16:17] offset:768
	global_load_dword v21, v137, s[16:17] offset:800
	global_load_dword v18, v137, s[16:17] offset:832
	global_load_dword v19, v137, s[16:17] offset:864
	global_load_dword v16, v137, s[16:17] offset:896
	global_load_dword v17, v137, s[16:17] offset:928
	global_load_dword v14, v137, s[16:17] offset:960
	global_load_dword v15, v137, s[16:17] offset:992
	s_waitcnt vmcnt(32)
	v_and_b32_e32 v12, 0x7fffffff, v12
	v_and_b32_e32 v11, 0x7fffffff, v11
	s_nop 1
	v_max_f32_dpp v12, v12, v12 quad_perm:[1,0,3,2] row_mask:0xf bank_mask:0xf
	v_max_f32_dpp v11, v11, v11 quad_perm:[1,0,3,2] row_mask:0xf bank_mask:0xf
	s_nop 1
	v_max_f32_dpp v12, v12, v12 quad_perm:[2,3,0,1] row_mask:0xf bank_mask:0xf
	v_max_f32_dpp v11, v11, v11 quad_perm:[2,3,0,1] row_mask:0xf bank_mask:0xf
	s_nop 1
	v_max_f32_dpp v12, v12, v12 row_half_mirror row_mask:0xf bank_mask:0xf
	v_max_f32_dpp v11, v11, v11 row_half_mirror row_mask:0xf bank_mask:0xf
	s_nop 1
	v_max_f32_dpp v12, v12, v12 row_mirror row_mask:0xf bank_mask:0xf
	v_max_f32_dpp v11, v11, v11 row_mirror row_mask:0xf bank_mask:0xf
	s_nop 1
	v_readlane_b32 s18, v12, 0
	v_readlane_b32 s19, v12, 16
	v_readlane_b32 s20, v12, 32
	v_readlane_b32 s21, v12, 48
	v_mov_b32_e32 v12, s18
	v_max_f32_e32 v12, s19, v12
	v_max_f32_e32 v12, s20, v12
	v_max_f32_e32 v12, s21, v12
	v_readlane_b32 s18, v11, 0
	v_readlane_b32 s19, v11, 16
	v_readlane_b32 s20, v11, 32
	v_readlane_b32 s21, v11, 48
	v_mov_b32_e32 v11, s18
	v_max_f32_e32 v11, s19, v11
	v_max_f32_e32 v11, s20, v11
	v_max_f32_e32 v11, s21, v11
	v_add_u32_e32 v0, 0xffffff40, v10
	v_sub_u32_e32 v1, 0xc0, v10
	v_max_i32_e32 v2, v0, v1
	v_cmp_lt_u32_e32 vcc, 7, v2
	s_and_saveexec_b64 s[18:19], vcc
	s_cbranch_execz .LBB0_103
	v_cmp_lt_u32_e32 vcc, 11, v2
	v_mov_b32_e32 v0, 8
	s_and_saveexec_b64 s[20:21], vcc
	s_cbranch_execz .LBB0_102
	v_cmp_lt_u32_e32 vcc, 15, v2
	v_mov_b32_e32 v0, 9
	s_and_saveexec_b64 s[22:23], vcc
	s_cbranch_execz .LBB0_101
	v_cmp_lt_u32_e32 vcc, 22, v2
	v_mov_b32_e32 v0, 10
	s_and_saveexec_b64 s[28:29], vcc
	s_movk_i32 s42, 0x5b
	v_cmp_gt_u32_e32 vcc, s42, v2
	s_nop 1
	v_cndmask_b32_e64 v0, 15, 14, vcc
	v_cmp_lt_u32_e32 vcc, 63, v2
	s_nop 1
	v_cndmask_b32_e32 v0, 13, v0, vcc
	v_cmp_lt_u32_e32 vcc, 45, v2
	s_nop 1
	v_cndmask_b32_e32 v0, 12, v0, vcc
	v_cmp_lt_u32_e32 vcc, 31, v2
	s_nop 1
	v_cndmask_b32_e32 v0, 11, v0, vcc
	s_or_b64 exec, exec, s[28:29]
